# unit-start vmcnt waits sized by the previous unit's kind (any grid size): 8 stores behind a differential unit, 4 behind a window unit
# speedup vs baseline: 1.0045x; 1.0045x over previous
; __global__ void __launch_bounds__(NWAVES * 64, 2) mk_fwd(Args args) {
;     ...
;             attn_body::bf16x8 qfr[4]; bool pref = false;
;             for (int v = vcu; v < 256; v += G) {
;                 for (int i = 0; i < 12; ++i) {
;                     long rowbase; int qb, t0, qc, kc, vc, oc; bool win; float s2, sink2; bf16* Ob;
;                     if (i < 8) {
;                         const int s = v & 7, bhv = (v >> 3) + 32 * (i >> 2), ii = i & 3, b = bhv >> 4, h = (bhv >> 2) & 3, c = (bhv >> 1) & 1, vh = bhv & 1;
;                         qb = (ii == 0) ? s : (ii == 1) ? 15 - s : (ii == 2) ? 16 + s : 31 - s; t0 = 0; win = false; rowbase = (long)b * SEQ;
;                         qc = 768 + h * 128 + c * 64; kc = 1280 + h * 128 + c * 64; vc = 1792 + h * 128 + vh * 64; oc = h * 128 + vh * 64; Ob = c ? OD1 : OD0;
;                         s2 = exp2f(-8.0f * (float)(9 + h) / 12.0f) * LOG2E; sink2 = -INFINITY;
;                     } else {
;                         const int ui = v * 4 + (i - 8), hq = (ui >> 5) & 7, b = ui >> 8; qb = ui & 31; t0 = qb > 0 ? 4 * qb - 2 : 0; win = true; rowbase = (long)b * SEQ;
;                         qc = hq * 64; kc = 512 + (hq >> 2) * 64; vc = 640 + (hq >> 2) * 64; oc = hq * 64; Ob = OA;
;                         s2 = exp2f(-8.0f * (float)(1 + hq) / 12.0f) * LOG2E; sink2 = ap->in[9][l * 8 + hq] * LOG2E;
;                     }
;                     int vn = v, in = i + 1; if (in == 12) { in = 0; vn = v + G; }
;                     if (vn >= 256) in = -1;
;                     attn_body::attn_unit<60>(rowbase, qb, t0, win, win ? nomax_swa : nomax_diff, (const attn_body::bf16*)QKV + qc, (const attn_body::bf16*)QKV + kc, (const attn_body::bf16*)QKV + vc, (attn_body::bf16*)Ob + oc, s2, sink2, (char*)lds,
;                         qfr, pref, (const attn_body::bf16*)QKV, vn, in);
;                     pref = in >= 0;
.LBB0_249:
	s_sub_u32 s42, s85, 1
	s_cmp_lt_u32 s42, 3
	s_cbranch_scc1 .Lmy_lh8
	s_cmp_eq_u32 s85, 8
	s_cbranch_scc1 .Lmy_lh8
	s_waitcnt vmcnt(4)
	s_branch .Lmy_lhd
.Lmy_lh8:
	s_waitcnt vmcnt(8)

; #define WAIT_BAR(N) asm volatile("s_waitcnt vmcnt(" #N ") lgkmcnt(0)\n\ts_barrier":::"memory")
;   #define DMA_K(t,slot) glds16(ksrc+(long)(t)*KVBLK*PIN,(unsigned)__builtin_amdgcn_readfirstlane(kdst+(slot)))
; template<int THRL> __device__ __forceinline__ void attn_unit(long rowbase,int qb,int t0,bool WIN,bool NOMAX,const bf16*Qc,const bf16*__restrict__ Kc,const bf16*__restrict__ Vc,bf16*Oc,float s2,float sink2,char*shm,
;     bf16x8 (&qr)[4],bool pref,const bf16*qkvb,int vn,int in_){
;     ...
;   if(!pref){ DMA_K(2,2*SLOTB);
;     WAIT_BAR(3); }
;   else { WAIT_BAR(5); }
.LBB0_264:
	s_sub_u32 s38, s85, 1
	s_cmp_lt_u32 s38, 3
	s_cbranch_scc1 .Lmy_wb10
	s_cmp_eq_u32 s85, 8
	s_cbranch_scc1 .Lmy_wb10
	s_waitcnt vmcnt(6) lgkmcnt(0)
	s_branch .Lmy_wbd
.Lmy_wb10:
	s_waitcnt vmcnt(10) lgkmcnt(0)
